# conv1d fast path: 16-row blocks for latent rows (19 row loads in flight, one wait per 16 outputs), 8-row path kept for remainders and context rows; otherwise v20
# baseline (speedup 1.0000x reference)
.Lc1_top:
	v_readfirstlane_b32 s84, v43
	v_readfirstlane_b32 s85, v104
	v_readfirstlane_b32 s88, v36
	v_readfirstlane_b32 s94, v56
	v_readfirstlane_b32 s95, v57
	v_lshlrev_b32_e32 v252, 1, v36
	s_nop 1
	s_lshl_b32 s88, s88, 1
	v_subrev_u32_e32 v252, s88, v252
	s_add_u32 s91, s84, 16
	s_cmp_gt_u32 s91, s85
	s_cbranch_scc1 .Lc1_8
	s_cmp_gt_u32 s91, 0x10000
	s_cbranch_scc1 .Lc1_8
	s_and_b32 s91, s84, 0x1fff
	s_cmp_lt_u32 s91, 2
	s_cbranch_scc1 .Lc1_8
	s_cmp_gt_u32 s91, 0x1fef
	s_cbranch_scc1 .Lc1_8
	v_readfirstlane_b32 s86, v54
	v_readfirstlane_b32 s87, v55
	s_nop 1
	s_add_u32 s86, s86, s88
	s_addc_u32 s87, s87, 0
	s_sub_u32 s92, s86, 0x6800
	s_subb_u32 s93, s87, 0
	global_load_dwordx2 v[112:113], v252, s[92:93]
	s_add_u32 s92, s92, 0x3400
	s_addc_u32 s93, s93, 0
	global_load_dwordx2 v[116:117], v252, s[92:93]
	s_add_u32 s92, s92, 0x3400
	s_addc_u32 s93, s93, 0
	global_load_dwordx2 v[120:121], v252, s[92:93]
	s_add_u32 s92, s92, 0x3400
	s_addc_u32 s93, s93, 0
	global_load_dwordx2 v[124:125], v252, s[92:93]
	s_add_u32 s92, s92, 0x3400
	s_addc_u32 s93, s93, 0
	global_load_dwordx2 v[128:129], v252, s[92:93]
	s_add_u32 s92, s92, 0x3400
	s_addc_u32 s93, s93, 0
	global_load_dwordx2 v[132:133], v252, s[92:93]
	s_add_u32 s92, s92, 0x3400
	s_addc_u32 s93, s93, 0
	global_load_dwordx2 v[136:137], v252, s[92:93]
	s_add_u32 s92, s92, 0x3400
	s_addc_u32 s93, s93, 0
	global_load_dwordx2 v[140:141], v252, s[92:93]
	s_add_u32 s92, s92, 0x3400
	s_addc_u32 s93, s93, 0
	global_load_dwordx2 v[144:145], v252, s[92:93]
	s_add_u32 s92, s92, 0x3400
	s_addc_u32 s93, s93, 0
	global_load_dwordx2 v[148:149], v252, s[92:93]
	s_add_u32 s92, s92, 0x3400
	s_addc_u32 s93, s93, 0
	global_load_dwordx2 v[152:153], v252, s[92:93]
	s_add_u32 s92, s92, 0x3400
	s_addc_u32 s93, s93, 0
	global_load_dwordx2 v[156:157], v252, s[92:93]
	s_add_u32 s92, s92, 0x3400
	s_addc_u32 s93, s93, 0
	global_load_dwordx2 v[160:161], v252, s[92:93]
	s_add_u32 s92, s92, 0x3400
	s_addc_u32 s93, s93, 0
	global_load_dwordx2 v[164:165], v252, s[92:93]
	s_add_u32 s92, s92, 0x3400
	s_addc_u32 s93, s93, 0
	global_load_dwordx2 v[168:169], v252, s[92:93]
	s_add_u32 s92, s92, 0x3400
	s_addc_u32 s93, s93, 0
	global_load_dwordx2 v[172:173], v252, s[92:93]
	s_add_u32 s92, s92, 0x3400
	s_addc_u32 s93, s93, 0
	global_load_dwordx2 v[176:177], v252, s[92:93]
	s_add_u32 s92, s92, 0x3400
	s_addc_u32 s93, s93, 0
	global_load_dwordx2 v[180:181], v252, s[92:93]
	s_add_u32 s92, s92, 0x3400
	s_addc_u32 s93, s93, 0
	global_load_dwordx2 v[184:185], v252, s[92:93]
	s_waitcnt vmcnt(0)
	v_lshlrev_b32_e32 v114, 16, v113
	v_and_b32_e32 v115, 0xffff0000, v113
	v_and_b32_e32 v113, 0xffff0000, v112
	v_lshlrev_b32_e32 v112, 16, v112
	v_lshlrev_b32_e32 v118, 16, v117
	v_and_b32_e32 v119, 0xffff0000, v117
	v_and_b32_e32 v117, 0xffff0000, v116
	v_lshlrev_b32_e32 v116, 16, v116
	v_lshlrev_b32_e32 v122, 16, v121
	v_and_b32_e32 v123, 0xffff0000, v121
	v_and_b32_e32 v121, 0xffff0000, v120
	v_lshlrev_b32_e32 v120, 16, v120
	v_lshlrev_b32_e32 v126, 16, v125
	v_and_b32_e32 v127, 0xffff0000, v125
	v_and_b32_e32 v125, 0xffff0000, v124
	v_lshlrev_b32_e32 v124, 16, v124
	v_lshlrev_b32_e32 v130, 16, v129
	v_and_b32_e32 v131, 0xffff0000, v129
	v_and_b32_e32 v129, 0xffff0000, v128
	v_lshlrev_b32_e32 v128, 16, v128
	v_lshlrev_b32_e32 v134, 16, v133
	v_and_b32_e32 v135, 0xffff0000, v133
	v_and_b32_e32 v133, 0xffff0000, v132
	v_lshlrev_b32_e32 v132, 16, v132
	v_lshlrev_b32_e32 v138, 16, v137
	v_and_b32_e32 v139, 0xffff0000, v137
	v_and_b32_e32 v137, 0xffff0000, v136
	v_lshlrev_b32_e32 v136, 16, v136
	v_lshlrev_b32_e32 v142, 16, v141
	v_and_b32_e32 v143, 0xffff0000, v141
	v_and_b32_e32 v141, 0xffff0000, v140
	v_lshlrev_b32_e32 v140, 16, v140
	v_lshlrev_b32_e32 v146, 16, v145
	v_and_b32_e32 v147, 0xffff0000, v145
	v_and_b32_e32 v145, 0xffff0000, v144
	v_lshlrev_b32_e32 v144, 16, v144
	v_lshlrev_b32_e32 v150, 16, v149
	v_and_b32_e32 v151, 0xffff0000, v149
	v_and_b32_e32 v149, 0xffff0000, v148
	v_lshlrev_b32_e32 v148, 16, v148
	v_lshlrev_b32_e32 v154, 16, v153
	v_and_b32_e32 v155, 0xffff0000, v153
	v_and_b32_e32 v153, 0xffff0000, v152
	v_lshlrev_b32_e32 v152, 16, v152
	v_lshlrev_b32_e32 v158, 16, v157
	v_and_b32_e32 v159, 0xffff0000, v157
	v_and_b32_e32 v157, 0xffff0000, v156
	v_lshlrev_b32_e32 v156, 16, v156
	v_lshlrev_b32_e32 v162, 16, v161
	v_and_b32_e32 v163, 0xffff0000, v161
	v_and_b32_e32 v161, 0xffff0000, v160
	v_lshlrev_b32_e32 v160, 16, v160
	v_lshlrev_b32_e32 v166, 16, v165
	v_and_b32_e32 v167, 0xffff0000, v165
	v_and_b32_e32 v165, 0xffff0000, v164
	v_lshlrev_b32_e32 v164, 16, v164
	v_lshlrev_b32_e32 v170, 16, v169
	v_and_b32_e32 v171, 0xffff0000, v169
	v_and_b32_e32 v169, 0xffff0000, v168
	v_lshlrev_b32_e32 v168, 16, v168
	v_lshlrev_b32_e32 v174, 16, v173
	v_and_b32_e32 v175, 0xffff0000, v173
	v_and_b32_e32 v173, 0xffff0000, v172
	v_lshlrev_b32_e32 v172, 16, v172
	v_lshlrev_b32_e32 v178, 16, v177
	v_and_b32_e32 v179, 0xffff0000, v177
	v_and_b32_e32 v177, 0xffff0000, v176
	v_lshlrev_b32_e32 v176, 16, v176
	v_lshlrev_b32_e32 v182, 16, v181
	v_and_b32_e32 v183, 0xffff0000, v181
	v_and_b32_e32 v181, 0xffff0000, v180
	v_lshlrev_b32_e32 v180, 16, v180
	v_lshlrev_b32_e32 v186, 16, v185
	v_and_b32_e32 v187, 0xffff0000, v185
	v_and_b32_e32 v185, 0xffff0000, v184
	v_lshlrev_b32_e32 v184, 16, v184
	v_pk_fma_f32 v[112:113], v[0:1], v[112:113], v[16:17]
	v_pk_fma_f32 v[114:115], v[2:3], v[114:115], v[18:19]
	v_pk_fma_f32 v[112:113], v[4:5], v[116:117], v[112:113]
	v_pk_fma_f32 v[114:115], v[6:7], v[118:119], v[114:115]
	v_pk_fma_f32 v[112:113], v[8:9], v[120:121], v[112:113]
	v_pk_fma_f32 v[114:115], v[10:11], v[122:123], v[114:115]
	v_pk_fma_f32 v[112:113], v[12:13], v[124:125], v[112:113]
	v_pk_fma_f32 v[114:115], v[14:15], v[126:127], v[114:115]
	v_cvt_pk_bf16_f32 v112, v112, v113
	v_cvt_pk_bf16_f32 v113, v114, v115
	global_store_dwordx2 v252, v[112:113], s[94:95]
	s_add_u32 s94, s94, 0xa00
	s_addc_u32 s95, s95, 0
	v_pk_fma_f32 v[116:117], v[0:1], v[116:117], v[16:17]
	v_pk_fma_f32 v[118:119], v[2:3], v[118:119], v[18:19]
	v_pk_fma_f32 v[116:117], v[4:5], v[120:121], v[116:117]
	v_pk_fma_f32 v[118:119], v[6:7], v[122:123], v[118:119]
	v_pk_fma_f32 v[116:117], v[8:9], v[124:125], v[116:117]
	v_pk_fma_f32 v[118:119], v[10:11], v[126:127], v[118:119]
	v_pk_fma_f32 v[116:117], v[12:13], v[128:129], v[116:117]
	v_pk_fma_f32 v[118:119], v[14:15], v[130:131], v[118:119]
	v_cvt_pk_bf16_f32 v116, v116, v117
	v_cvt_pk_bf16_f32 v117, v118, v119
	global_store_dwordx2 v252, v[116:117], s[94:95]
	s_add_u32 s94, s94, 0xa00
	s_addc_u32 s95, s95, 0
	v_pk_fma_f32 v[120:121], v[0:1], v[120:121], v[16:17]
	v_pk_fma_f32 v[122:123], v[2:3], v[122:123], v[18:19]
	v_pk_fma_f32 v[120:121], v[4:5], v[124:125], v[120:121]
	v_pk_fma_f32 v[122:123], v[6:7], v[126:127], v[122:123]
	v_pk_fma_f32 v[120:121], v[8:9], v[128:129], v[120:121]
	v_pk_fma_f32 v[122:123], v[10:11], v[130:131], v[122:123]
	v_pk_fma_f32 v[120:121], v[12:13], v[132:133], v[120:121]
	v_pk_fma_f32 v[122:123], v[14:15], v[134:135], v[122:123]
	v_cvt_pk_bf16_f32 v120, v120, v121
	v_cvt_pk_bf16_f32 v121, v122, v123
	global_store_dwordx2 v252, v[120:121], s[94:95]
	s_add_u32 s94, s94, 0xa00
	s_addc_u32 s95, s95, 0
	v_pk_fma_f32 v[124:125], v[0:1], v[124:125], v[16:17]
	v_pk_fma_f32 v[126:127], v[2:3], v[126:127], v[18:19]
	v_pk_fma_f32 v[124:125], v[4:5], v[128:129], v[124:125]
	v_pk_fma_f32 v[126:127], v[6:7], v[130:131], v[126:127]
	v_pk_fma_f32 v[124:125], v[8:9], v[132:133], v[124:125]
	v_pk_fma_f32 v[126:127], v[10:11], v[134:135], v[126:127]
	v_pk_fma_f32 v[124:125], v[12:13], v[136:137], v[124:125]
	v_pk_fma_f32 v[126:127], v[14:15], v[138:139], v[126:127]
	v_cvt_pk_bf16_f32 v124, v124, v125
	v_cvt_pk_bf16_f32 v125, v126, v127
	global_store_dwordx2 v252, v[124:125], s[94:95]
	s_add_u32 s94, s94, 0xa00
	s_addc_u32 s95, s95, 0
	v_pk_fma_f32 v[128:129], v[0:1], v[128:129], v[16:17]
	v_pk_fma_f32 v[130:131], v[2:3], v[130:131], v[18:19]
	v_pk_fma_f32 v[128:129], v[4:5], v[132:133], v[128:129]
	v_pk_fma_f32 v[130:131], v[6:7], v[134:135], v[130:131]
	v_pk_fma_f32 v[128:129], v[8:9], v[136:137], v[128:129]
	v_pk_fma_f32 v[130:131], v[10:11], v[138:139], v[130:131]
	v_pk_fma_f32 v[128:129], v[12:13], v[140:141], v[128:129]
	v_pk_fma_f32 v[130:131], v[14:15], v[142:143], v[130:131]
	v_cvt_pk_bf16_f32 v128, v128, v129
	v_cvt_pk_bf16_f32 v129, v130, v131
	global_store_dwordx2 v252, v[128:129], s[94:95]
	s_add_u32 s94, s94, 0xa00
	s_addc_u32 s95, s95, 0
	v_pk_fma_f32 v[132:133], v[0:1], v[132:133], v[16:17]
	v_pk_fma_f32 v[134:135], v[2:3], v[134:135], v[18:19]
	v_pk_fma_f32 v[132:133], v[4:5], v[136:137], v[132:133]
	v_pk_fma_f32 v[134:135], v[6:7], v[138:139], v[134:135]
	v_pk_fma_f32 v[132:133], v[8:9], v[140:141], v[132:133]
	v_pk_fma_f32 v[134:135], v[10:11], v[142:143], v[134:135]
	v_pk_fma_f32 v[132:133], v[12:13], v[144:145], v[132:133]
	v_pk_fma_f32 v[134:135], v[14:15], v[146:147], v[134:135]
	v_cvt_pk_bf16_f32 v132, v132, v133
	v_cvt_pk_bf16_f32 v133, v134, v135
	global_store_dwordx2 v252, v[132:133], s[94:95]
	s_add_u32 s94, s94, 0xa00
	s_addc_u32 s95, s95, 0
	v_pk_fma_f32 v[136:137], v[0:1], v[136:137], v[16:17]
	v_pk_fma_f32 v[138:139], v[2:3], v[138:139], v[18:19]
	v_pk_fma_f32 v[136:137], v[4:5], v[140:141], v[136:137]
	v_pk_fma_f32 v[138:139], v[6:7], v[142:143], v[138:139]
	v_pk_fma_f32 v[136:137], v[8:9], v[144:145], v[136:137]
	v_pk_fma_f32 v[138:139], v[10:11], v[146:147], v[138:139]
	v_pk_fma_f32 v[136:137], v[12:13], v[148:149], v[136:137]
	v_pk_fma_f32 v[138:139], v[14:15], v[150:151], v[138:139]
	v_cvt_pk_bf16_f32 v136, v136, v137
	v_cvt_pk_bf16_f32 v137, v138, v139
	global_store_dwordx2 v252, v[136:137], s[94:95]
	s_add_u32 s94, s94, 0xa00
	s_addc_u32 s95, s95, 0
	v_pk_fma_f32 v[140:141], v[0:1], v[140:141], v[16:17]
	v_pk_fma_f32 v[142:143], v[2:3], v[142:143], v[18:19]
	v_pk_fma_f32 v[140:141], v[4:5], v[144:145], v[140:141]
	v_pk_fma_f32 v[142:143], v[6:7], v[146:147], v[142:143]
	v_pk_fma_f32 v[140:141], v[8:9], v[148:149], v[140:141]
	v_pk_fma_f32 v[142:143], v[10:11], v[150:151], v[142:143]
	v_pk_fma_f32 v[140:141], v[12:13], v[152:153], v[140:141]
	v_pk_fma_f32 v[142:143], v[14:15], v[154:155], v[142:143]
	v_cvt_pk_bf16_f32 v140, v140, v141
	v_cvt_pk_bf16_f32 v141, v142, v143
	global_store_dwordx2 v252, v[140:141], s[94:95]
	s_add_u32 s94, s94, 0xa00
	s_addc_u32 s95, s95, 0
	v_pk_fma_f32 v[144:145], v[0:1], v[144:145], v[16:17]
	v_pk_fma_f32 v[146:147], v[2:3], v[146:147], v[18:19]
	v_pk_fma_f32 v[144:145], v[4:5], v[148:149], v[144:145]
	v_pk_fma_f32 v[146:147], v[6:7], v[150:151], v[146:147]
	v_pk_fma_f32 v[144:145], v[8:9], v[152:153], v[144:145]
	v_pk_fma_f32 v[146:147], v[10:11], v[154:155], v[146:147]
	v_pk_fma_f32 v[144:145], v[12:13], v[156:157], v[144:145]
	v_pk_fma_f32 v[146:147], v[14:15], v[158:159], v[146:147]
	v_cvt_pk_bf16_f32 v144, v144, v145
	v_cvt_pk_bf16_f32 v145, v146, v147
	global_store_dwordx2 v252, v[144:145], s[94:95]
	s_add_u32 s94, s94, 0xa00
	s_addc_u32 s95, s95, 0
	v_pk_fma_f32 v[148:149], v[0:1], v[148:149], v[16:17]
	v_pk_fma_f32 v[150:151], v[2:3], v[150:151], v[18:19]
	v_pk_fma_f32 v[148:149], v[4:5], v[152:153], v[148:149]
	v_pk_fma_f32 v[150:151], v[6:7], v[154:155], v[150:151]
	v_pk_fma_f32 v[148:149], v[8:9], v[156:157], v[148:149]
	v_pk_fma_f32 v[150:151], v[10:11], v[158:159], v[150:151]
	v_pk_fma_f32 v[148:149], v[12:13], v[160:161], v[148:149]
	v_pk_fma_f32 v[150:151], v[14:15], v[162:163], v[150:151]
	v_cvt_pk_bf16_f32 v148, v148, v149
	v_cvt_pk_bf16_f32 v149, v150, v151
	global_store_dwordx2 v252, v[148:149], s[94:95]
	s_add_u32 s94, s94, 0xa00
	s_addc_u32 s95, s95, 0
	v_pk_fma_f32 v[152:153], v[0:1], v[152:153], v[16:17]
	v_pk_fma_f32 v[154:155], v[2:3], v[154:155], v[18:19]
	v_pk_fma_f32 v[152:153], v[4:5], v[156:157], v[152:153]
	v_pk_fma_f32 v[154:155], v[6:7], v[158:159], v[154:155]
	v_pk_fma_f32 v[152:153], v[8:9], v[160:161], v[152:153]
	v_pk_fma_f32 v[154:155], v[10:11], v[162:163], v[154:155]
	v_pk_fma_f32 v[152:153], v[12:13], v[164:165], v[152:153]
	v_pk_fma_f32 v[154:155], v[14:15], v[166:167], v[154:155]
	v_cvt_pk_bf16_f32 v152, v152, v153
	v_cvt_pk_bf16_f32 v153, v154, v155
	global_store_dwordx2 v252, v[152:153], s[94:95]
	s_add_u32 s94, s94, 0xa00
	s_addc_u32 s95, s95, 0
	v_pk_fma_f32 v[156:157], v[0:1], v[156:157], v[16:17]
	v_pk_fma_f32 v[158:159], v[2:3], v[158:159], v[18:19]
	v_pk_fma_f32 v[156:157], v[4:5], v[160:161], v[156:157]
	v_pk_fma_f32 v[158:159], v[6:7], v[162:163], v[158:159]
	v_pk_fma_f32 v[156:157], v[8:9], v[164:165], v[156:157]
	v_pk_fma_f32 v[158:159], v[10:11], v[166:167], v[158:159]
	v_pk_fma_f32 v[156:157], v[12:13], v[168:169], v[156:157]
	v_pk_fma_f32 v[158:159], v[14:15], v[170:171], v[158:159]
	v_cvt_pk_bf16_f32 v156, v156, v157
	v_cvt_pk_bf16_f32 v157, v158, v159
	global_store_dwordx2 v252, v[156:157], s[94:95]
	s_add_u32 s94, s94, 0xa00
	s_addc_u32 s95, s95, 0
	v_pk_fma_f32 v[160:161], v[0:1], v[160:161], v[16:17]
	v_pk_fma_f32 v[162:163], v[2:3], v[162:163], v[18:19]
	v_pk_fma_f32 v[160:161], v[4:5], v[164:165], v[160:161]
	v_pk_fma_f32 v[162:163], v[6:7], v[166:167], v[162:163]
	v_pk_fma_f32 v[160:161], v[8:9], v[168:169], v[160:161]
	v_pk_fma_f32 v[162:163], v[10:11], v[170:171], v[162:163]
	v_pk_fma_f32 v[160:161], v[12:13], v[172:173], v[160:161]
	v_pk_fma_f32 v[162:163], v[14:15], v[174:175], v[162:163]
	v_cvt_pk_bf16_f32 v160, v160, v161
	v_cvt_pk_bf16_f32 v161, v162, v163
	global_store_dwordx2 v252, v[160:161], s[94:95]
	s_add_u32 s94, s94, 0xa00
	s_addc_u32 s95, s95, 0
	v_pk_fma_f32 v[164:165], v[0:1], v[164:165], v[16:17]
	v_pk_fma_f32 v[166:167], v[2:3], v[166:167], v[18:19]
	v_pk_fma_f32 v[164:165], v[4:5], v[168:169], v[164:165]
	v_pk_fma_f32 v[166:167], v[6:7], v[170:171], v[166:167]
	v_pk_fma_f32 v[164:165], v[8:9], v[172:173], v[164:165]
	v_pk_fma_f32 v[166:167], v[10:11], v[174:175], v[166:167]
	v_pk_fma_f32 v[164:165], v[12:13], v[176:177], v[164:165]
	v_pk_fma_f32 v[166:167], v[14:15], v[178:179], v[166:167]
	v_cvt_pk_bf16_f32 v164, v164, v165
	v_cvt_pk_bf16_f32 v165, v166, v167
	global_store_dwordx2 v252, v[164:165], s[94:95]
	s_add_u32 s94, s94, 0xa00
	s_addc_u32 s95, s95, 0
	v_pk_fma_f32 v[168:169], v[0:1], v[168:169], v[16:17]
	v_pk_fma_f32 v[170:171], v[2:3], v[170:171], v[18:19]
	v_pk_fma_f32 v[168:169], v[4:5], v[172:173], v[168:169]
	v_pk_fma_f32 v[170:171], v[6:7], v[174:175], v[170:171]
	v_pk_fma_f32 v[168:169], v[8:9], v[176:177], v[168:169]
	v_pk_fma_f32 v[170:171], v[10:11], v[178:179], v[170:171]
	v_pk_fma_f32 v[168:169], v[12:13], v[180:181], v[168:169]
	v_pk_fma_f32 v[170:171], v[14:15], v[182:183], v[170:171]
	v_cvt_pk_bf16_f32 v168, v168, v169
	v_cvt_pk_bf16_f32 v169, v170, v171
	global_store_dwordx2 v252, v[168:169], s[94:95]
	s_add_u32 s94, s94, 0xa00
	s_addc_u32 s95, s95, 0
	v_pk_fma_f32 v[172:173], v[0:1], v[172:173], v[16:17]
	v_pk_fma_f32 v[174:175], v[2:3], v[174:175], v[18:19]
	v_pk_fma_f32 v[172:173], v[4:5], v[176:177], v[172:173]
	v_pk_fma_f32 v[174:175], v[6:7], v[178:179], v[174:175]
	v_pk_fma_f32 v[172:173], v[8:9], v[180:181], v[172:173]
	v_pk_fma_f32 v[174:175], v[10:11], v[182:183], v[174:175]
	v_pk_fma_f32 v[172:173], v[12:13], v[184:185], v[172:173]
	v_pk_fma_f32 v[174:175], v[14:15], v[186:187], v[174:175]
	v_cvt_pk_bf16_f32 v172, v172, v173
	v_cvt_pk_bf16_f32 v173, v174, v175
	global_store_dwordx2 v252, v[172:173], s[94:95]
	s_mov_b32 s66, 0x34000
	s_mov_b32 s67, 0
	s_mov_b32 s68, 0xa000
	s_mov_b32 s69, 0
	v_add_u32_e32 v43, 16, v43
	v_lshl_add_u64 v[54:55], v[54:55], 0, s[66:67]
	v_lshl_add_u64 v[56:57], v[56:57], 0, s[68:69]
	s_add_u32 s84, s84, 16
	s_cmp_lt_u32 s84, s85
	s_cbranch_scc1 .Lc1_top
	s_branch .LBB0_344
.Lc1_8:
	s_add_u32 s91, s84, 8
	s_cmp_gt_u32 s91, s85
	s_cbranch_scc1 .LBB0_360
	s_cmp_ge_u32 s84, 0x10000
	s_cbranch_scc1 .Lc1_ctx
	s_cmp_gt_u32 s91, 0x10000
	s_cbranch_scc1 .LBB0_360
	s_and_b32 s91, s84, 0x1fff
	s_cmp_lt_u32 s91, 2
	s_cbranch_scc1 .LBB0_360
	s_cmp_gt_u32 s91, 0x1ff7
	s_cbranch_scc1 .LBB0_360
	v_readfirstlane_b32 s86, v54
	v_readfirstlane_b32 s87, v55
	s_nop 1
	s_add_u32 s86, s86, s88
	s_addc_u32 s87, s87, 0
	s_sub_u32 s92, s86, 0x6800
	s_subb_u32 s93, s87, 0
	global_load_dwordx2 v[208:209], v252, s[92:93]
	s_add_u32 s92, s92, 0x3400
	s_addc_u32 s93, s93, 0
	global_load_dwordx2 v[212:213], v252, s[92:93]
	s_add_u32 s92, s92, 0x3400
	s_addc_u32 s93, s93, 0
	global_load_dwordx2 v[216:217], v252, s[92:93]
	s_add_u32 s92, s92, 0x3400
	s_addc_u32 s93, s93, 0
	global_load_dwordx2 v[220:221], v252, s[92:93]
	s_add_u32 s92, s92, 0x3400
	s_addc_u32 s93, s93, 0
	global_load_dwordx2 v[224:225], v252, s[92:93]
	s_add_u32 s92, s92, 0x3400
	s_addc_u32 s93, s93, 0
	global_load_dwordx2 v[228:229], v252, s[92:93]
	s_add_u32 s92, s92, 0x3400
	s_addc_u32 s93, s93, 0
	global_load_dwordx2 v[232:233], v252, s[92:93]
	s_add_u32 s92, s92, 0x3400
	s_addc_u32 s93, s93, 0
	global_load_dwordx2 v[236:237], v252, s[92:93]
	s_add_u32 s92, s92, 0x3400
	s_addc_u32 s93, s93, 0
	global_load_dwordx2 v[240:241], v252, s[92:93]
	s_add_u32 s92, s92, 0x3400
	s_addc_u32 s93, s93, 0
	global_load_dwordx2 v[244:245], v252, s[92:93]
	s_add_u32 s92, s92, 0x3400
	s_addc_u32 s93, s93, 0
	global_load_dwordx2 v[248:249], v252, s[92:93]
	s_waitcnt vmcnt(0)
	v_lshlrev_b32_e32 v210, 16, v209
	v_and_b32_e32 v211, 0xffff0000, v209
	v_and_b32_e32 v209, 0xffff0000, v208
	v_lshlrev_b32_e32 v208, 16, v208
	v_lshlrev_b32_e32 v214, 16, v213
	v_and_b32_e32 v215, 0xffff0000, v213
	v_and_b32_e32 v213, 0xffff0000, v212
	v_lshlrev_b32_e32 v212, 16, v212
	v_lshlrev_b32_e32 v218, 16, v217
	v_and_b32_e32 v219, 0xffff0000, v217
	v_and_b32_e32 v217, 0xffff0000, v216
	v_lshlrev_b32_e32 v216, 16, v216
	v_lshlrev_b32_e32 v222, 16, v221
	v_and_b32_e32 v223, 0xffff0000, v221
	v_and_b32_e32 v221, 0xffff0000, v220
	v_lshlrev_b32_e32 v220, 16, v220
	v_lshlrev_b32_e32 v226, 16, v225
	v_and_b32_e32 v227, 0xffff0000, v225
	v_and_b32_e32 v225, 0xffff0000, v224
	v_lshlrev_b32_e32 v224, 16, v224
	v_lshlrev_b32_e32 v230, 16, v229
	v_and_b32_e32 v231, 0xffff0000, v229
	v_and_b32_e32 v229, 0xffff0000, v228
	v_lshlrev_b32_e32 v228, 16, v228
	v_lshlrev_b32_e32 v234, 16, v233
	v_and_b32_e32 v235, 0xffff0000, v233
	v_and_b32_e32 v233, 0xffff0000, v232
	v_lshlrev_b32_e32 v232, 16, v232
	v_lshlrev_b32_e32 v238, 16, v237
	v_and_b32_e32 v239, 0xffff0000, v237
	v_and_b32_e32 v237, 0xffff0000, v236
	v_lshlrev_b32_e32 v236, 16, v236
	v_lshlrev_b32_e32 v242, 16, v241
	v_and_b32_e32 v243, 0xffff0000, v241
	v_and_b32_e32 v241, 0xffff0000, v240
	v_lshlrev_b32_e32 v240, 16, v240
	v_lshlrev_b32_e32 v246, 16, v245
	v_and_b32_e32 v247, 0xffff0000, v245
	v_and_b32_e32 v245, 0xffff0000, v244
	v_lshlrev_b32_e32 v244, 16, v244
	v_lshlrev_b32_e32 v250, 16, v249
	v_and_b32_e32 v251, 0xffff0000, v249
	v_and_b32_e32 v249, 0xffff0000, v248
	v_lshlrev_b32_e32 v248, 16, v248
	v_pk_fma_f32 v[208:209], v[0:1], v[208:209], v[16:17]
	v_pk_fma_f32 v[210:211], v[2:3], v[210:211], v[18:19]
	v_pk_fma_f32 v[208:209], v[4:5], v[212:213], v[208:209]
	v_pk_fma_f32 v[210:211], v[6:7], v[214:215], v[210:211]
	v_pk_fma_f32 v[208:209], v[8:9], v[216:217], v[208:209]
	v_pk_fma_f32 v[210:211], v[10:11], v[218:219], v[210:211]
	v_pk_fma_f32 v[208:209], v[12:13], v[220:221], v[208:209]
	v_pk_fma_f32 v[210:211], v[14:15], v[222:223], v[210:211]
	v_cvt_pk_bf16_f32 v208, v208, v209
	v_cvt_pk_bf16_f32 v209, v210, v211
	global_store_dwordx2 v252, v[208:209], s[94:95]
	s_add_u32 s94, s94, 0xa00
	s_addc_u32 s95, s95, 0
	v_pk_fma_f32 v[212:213], v[0:1], v[212:213], v[16:17]
	v_pk_fma_f32 v[214:215], v[2:3], v[214:215], v[18:19]
	v_pk_fma_f32 v[212:213], v[4:5], v[216:217], v[212:213]
	v_pk_fma_f32 v[214:215], v[6:7], v[218:219], v[214:215]
	v_pk_fma_f32 v[212:213], v[8:9], v[220:221], v[212:213]
	v_pk_fma_f32 v[214:215], v[10:11], v[222:223], v[214:215]
	v_pk_fma_f32 v[212:213], v[12:13], v[224:225], v[212:213]
	v_pk_fma_f32 v[214:215], v[14:15], v[226:227], v[214:215]
	v_cvt_pk_bf16_f32 v212, v212, v213
	v_cvt_pk_bf16_f32 v213, v214, v215
	global_store_dwordx2 v252, v[212:213], s[94:95]
	s_add_u32 s94, s94, 0xa00
	s_addc_u32 s95, s95, 0
	v_pk_fma_f32 v[216:217], v[0:1], v[216:217], v[16:17]
	v_pk_fma_f32 v[218:219], v[2:3], v[218:219], v[18:19]
	v_pk_fma_f32 v[216:217], v[4:5], v[220:221], v[216:217]
	v_pk_fma_f32 v[218:219], v[6:7], v[222:223], v[218:219]
	v_pk_fma_f32 v[216:217], v[8:9], v[224:225], v[216:217]
	v_pk_fma_f32 v[218:219], v[10:11], v[226:227], v[218:219]
	v_pk_fma_f32 v[216:217], v[12:13], v[228:229], v[216:217]
	v_pk_fma_f32 v[218:219], v[14:15], v[230:231], v[218:219]
	v_cvt_pk_bf16_f32 v216, v216, v217
	v_cvt_pk_bf16_f32 v217, v218, v219
	global_store_dwordx2 v252, v[216:217], s[94:95]
	s_add_u32 s94, s94, 0xa00
	s_addc_u32 s95, s95, 0
	v_pk_fma_f32 v[220:221], v[0:1], v[220:221], v[16:17]
	v_pk_fma_f32 v[222:223], v[2:3], v[222:223], v[18:19]
	v_pk_fma_f32 v[220:221], v[4:5], v[224:225], v[220:221]
	v_pk_fma_f32 v[222:223], v[6:7], v[226:227], v[222:223]
	v_pk_fma_f32 v[220:221], v[8:9], v[228:229], v[220:221]
	v_pk_fma_f32 v[222:223], v[10:11], v[230:231], v[222:223]
	v_pk_fma_f32 v[220:221], v[12:13], v[232:233], v[220:221]
	v_pk_fma_f32 v[222:223], v[14:15], v[234:235], v[222:223]
	v_cvt_pk_bf16_f32 v220, v220, v221
	v_cvt_pk_bf16_f32 v221, v222, v223
	global_store_dwordx2 v252, v[220:221], s[94:95]
	s_add_u32 s94, s94, 0xa00
	s_addc_u32 s95, s95, 0
	v_pk_fma_f32 v[224:225], v[0:1], v[224:225], v[16:17]
	v_pk_fma_f32 v[226:227], v[2:3], v[226:227], v[18:19]
	v_pk_fma_f32 v[224:225], v[4:5], v[228:229], v[224:225]
	v_pk_fma_f32 v[226:227], v[6:7], v[230:231], v[226:227]
	v_pk_fma_f32 v[224:225], v[8:9], v[232:233], v[224:225]
	v_pk_fma_f32 v[226:227], v[10:11], v[234:235], v[226:227]
	v_pk_fma_f32 v[224:225], v[12:13], v[236:237], v[224:225]
	v_pk_fma_f32 v[226:227], v[14:15], v[238:239], v[226:227]
	v_cvt_pk_bf16_f32 v224, v224, v225
	v_cvt_pk_bf16_f32 v225, v226, v227
	global_store_dwordx2 v252, v[224:225], s[94:95]
	s_add_u32 s94, s94, 0xa00
	s_addc_u32 s95, s95, 0
	v_pk_fma_f32 v[228:229], v[0:1], v[228:229], v[16:17]
	v_pk_fma_f32 v[230:231], v[2:3], v[230:231], v[18:19]
	v_pk_fma_f32 v[228:229], v[4:5], v[232:233], v[228:229]
	v_pk_fma_f32 v[230:231], v[6:7], v[234:235], v[230:231]
	v_pk_fma_f32 v[228:229], v[8:9], v[236:237], v[228:229]
	v_pk_fma_f32 v[230:231], v[10:11], v[238:239], v[230:231]
	v_pk_fma_f32 v[228:229], v[12:13], v[240:241], v[228:229]
	v_pk_fma_f32 v[230:231], v[14:15], v[242:243], v[230:231]
	v_cvt_pk_bf16_f32 v228, v228, v229
	v_cvt_pk_bf16_f32 v229, v230, v231
	global_store_dwordx2 v252, v[228:229], s[94:95]
	s_add_u32 s94, s94, 0xa00
	s_addc_u32 s95, s95, 0
	v_pk_fma_f32 v[232:233], v[0:1], v[232:233], v[16:17]
	v_pk_fma_f32 v[234:235], v[2:3], v[234:235], v[18:19]
	v_pk_fma_f32 v[232:233], v[4:5], v[236:237], v[232:233]
	v_pk_fma_f32 v[234:235], v[6:7], v[238:239], v[234:235]
	v_pk_fma_f32 v[232:233], v[8:9], v[240:241], v[232:233]
	v_pk_fma_f32 v[234:235], v[10:11], v[242:243], v[234:235]
	v_pk_fma_f32 v[232:233], v[12:13], v[244:245], v[232:233]
	v_pk_fma_f32 v[234:235], v[14:15], v[246:247], v[234:235]
	v_cvt_pk_bf16_f32 v232, v232, v233
	v_cvt_pk_bf16_f32 v233, v234, v235
	global_store_dwordx2 v252, v[232:233], s[94:95]
	s_add_u32 s94, s94, 0xa00
	s_addc_u32 s95, s95, 0
	v_pk_fma_f32 v[236:237], v[0:1], v[236:237], v[16:17]
	v_pk_fma_f32 v[238:239], v[2:3], v[238:239], v[18:19]
	v_pk_fma_f32 v[236:237], v[4:5], v[240:241], v[236:237]
	v_pk_fma_f32 v[238:239], v[6:7], v[242:243], v[238:239]
	v_pk_fma_f32 v[236:237], v[8:9], v[244:245], v[236:237]
	v_pk_fma_f32 v[238:239], v[10:11], v[246:247], v[238:239]
	v_pk_fma_f32 v[236:237], v[12:13], v[248:249], v[236:237]
	v_pk_fma_f32 v[238:239], v[14:15], v[250:251], v[238:239]
	v_cvt_pk_bf16_f32 v236, v236, v237
	v_cvt_pk_bf16_f32 v237, v238, v239
	global_store_dwordx2 v252, v[236:237], s[94:95]
	s_mov_b32 s66, 0x1a000
	s_mov_b32 s67, 0
	s_mov_b32 s68, 0x5000
	s_mov_b32 s69, 0
	v_add_u32_e32 v43, 8, v43
	v_lshl_add_u64 v[54:55], v[54:55], 0, s[66:67]
	v_lshl_add_u64 v[56:57], v[56:57], 0, s[68:69]
	s_add_u32 s84, s84, 8
	s_cmp_lt_u32 s84, s85
	s_cbranch_scc1 .Lc1_top
	s_branch .LBB0_344
